# P1/P4/P6 epilogues: leading half's align barrier sunk below its first epilogue loads (row scales / residual tile issued before the wait)
# baseline (speedup 1.0000x reference)
; #define PG8_STAGE(bufoff, gbase, voff) do { _Pragma("unroll") for (int _i = 0; _i < 2; ++_i) \
;         __builtin_amdgcn_global_load_lds((const unsigned*)((const char*)(gbase) + (voff)[_i]), (PG8_LAS unsigned*)(lds + (bufoff) + ldsw + _i * 8192), 16, 0, 0); } while (0)
; #define PG8_LDA(dst, b, h) do { _Pragma("unroll") for (int m = 0; m < 4; ++m) _Pragma("unroll") for (int k = 0; k < 2; ++k) dst[m][k] = *(const PG8_LAS bf16x8*)(lds + PG8_SA(b, h) + aoff + m * 2048 + k * 1024); } while (0)
; #define PG8_MMA(ai, bj, At, Bt) do { __builtin_amdgcn_s_setprio(1); _Pragma("unroll") for (int m = 0; m < 4; ++m) _Pragma("unroll") for (int n = 0; n < 2; ++n) _Pragma("unroll") for (int k = 0; k < 2; ++k) \
;         acc[ai][bj][m][n] = __builtin_amdgcn_mfma_f32_16x16x32_bf16(Bt[n][k], At[m][k], acc[ai][bj][m][n], 0, 0, 0); __builtin_amdgcn_s_setprio(0); } while (0)
; #define PG8_WAIT_V(n) asm volatile("s_waitcnt vmcnt(" #n ")" ::: "memory")
; #define PG8_WAIT_L(n) asm volatile("s_waitcnt lgkmcnt(" #n ")" ::: "memory")
; #define PG8_BAR __builtin_amdgcn_s_barrier()
; #define PG8_SCHED __builtin_amdgcn_sched_barrier(0)
; template <class Epi, class Sched, bool ALIGN_EPI = false, bool SP2 = false>
; __device__ __forceinline__ void gemm_phase(PG8_LAS unsigned char* lds, const Gemm g, const Sched& S, const Epi& E) {
;     ...
;             PG8_LDA(At, 1, 1); PG8_STAGE(PG8_SB(1, 0), b3, voffB); PG8_STAGE(PG8_SB(1, 1), b3 + hstep, voffB); PG8_STAGE(PG8_SA(1, 0), a3, voffA);
;             PG8_WAIT_V(8); PG8_WAIT_L(0); PG8_BAR; PG8_MMA(1, 0, At, B0); PG8_MMA(1, 1, At, B1); PG8_BAR; PG8_SCHED;
;     ...
;         if constexpr (ALIGN_EPI) { if (wr == 0) PG8_BAR; }
.Lnl_110_7:
	s_barrier
	s_waitcnt lgkmcnt(0)
	v_mfma_f32_16x16x32_bf16 v[94:97], v[146:149], v[186:189], v[94:97]
	v_mfma_f32_16x16x32_bf16 v[90:93], v[154:157], v[186:189], v[90:93]
	v_mfma_f32_16x16x32_bf16 v[86:89], v[146:149], v[194:197], v[86:89]
	v_mfma_f32_16x16x32_bf16 v[82:85], v[154:157], v[194:197], v[82:85]
	v_mfma_f32_16x16x32_bf16 v[78:81], v[146:149], v[202:205], v[78:81]
	v_mfma_f32_16x16x32_bf16 v[74:77], v[154:157], v[202:205], v[74:77]
	v_mfma_f32_16x16x32_bf16 v[70:73], v[146:149], v[212:215], v[70:73]
	v_mfma_f32_16x16x32_bf16 v[66:69], v[154:157], v[212:215], v[66:69]
	v_mfma_f32_16x16x32_bf16 v[94:97], v[150:153], v[190:193], v[94:97]
	v_mfma_f32_16x16x32_bf16 v[90:93], v[166:169], v[190:193], v[90:93]
	v_mfma_f32_16x16x32_bf16 v[86:89], v[150:153], v[198:201], v[86:89]
	v_mfma_f32_16x16x32_bf16 v[82:85], v[166:169], v[198:201], v[82:85]
	v_mfma_f32_16x16x32_bf16 v[78:81], v[150:153], v[208:211], v[78:81]
	v_mfma_f32_16x16x32_bf16 v[74:77], v[166:169], v[208:211], v[74:77]
	v_mfma_f32_16x16x32_bf16 v[70:73], v[150:153], v[216:219], v[70:73]
	v_mfma_f32_16x16x32_bf16 v[66:69], v[166:169], v[216:219], v[66:69]
	v_mfma_f32_16x16x32_bf16 v[30:33], v[170:173], v[186:189], v[30:33]
	v_mfma_f32_16x16x32_bf16 v[26:29], v[178:181], v[186:189], v[26:29]
	v_mfma_f32_16x16x32_bf16 v[22:25], v[170:173], v[194:197], v[22:25]
	v_mfma_f32_16x16x32_bf16 v[18:21], v[178:181], v[194:197], v[18:21]
	v_mfma_f32_16x16x32_bf16 v[14:17], v[170:173], v[202:205], v[14:17]
	v_mfma_f32_16x16x32_bf16 v[10:13], v[178:181], v[202:205], v[10:13]
	v_mfma_f32_16x16x32_bf16 v[6:9], v[170:173], v[212:215], v[6:9]
	v_mfma_f32_16x16x32_bf16 v[2:5], v[178:181], v[212:215], v[2:5]
	v_mfma_f32_16x16x32_bf16 v[30:33], v[174:177], v[190:193], v[30:33]
	v_mfma_f32_16x16x32_bf16 v[26:29], v[182:185], v[190:193], v[26:29]
	v_mfma_f32_16x16x32_bf16 v[22:25], v[174:177], v[198:201], v[22:25]
	v_mfma_f32_16x16x32_bf16 v[18:21], v[182:185], v[198:201], v[18:21]
	v_mfma_f32_16x16x32_bf16 v[14:17], v[174:177], v[208:211], v[14:17]
	v_mfma_f32_16x16x32_bf16 v[10:13], v[182:185], v[208:211], v[10:13]
	v_mfma_f32_16x16x32_bf16 v[6:9], v[174:177], v[216:219], v[6:9]
	v_mfma_f32_16x16x32_bf16 v[2:5], v[182:185], v[216:219], v[2:5]
	s_add_i32 s84, s84, 2
	s_add_u32 s6, s6, 0x100
	s_addc_u32 s7, s7, 0
	s_add_u32 s73, s73, 0x100
	s_addc_u32 s75, s75, 0
	s_cmp_gt_u32 s84, 13
	s_barrier
	s_cbranch_scc0 .LBB0_110
	s_mov_b32 s100, 0xbfb8aa3b
	s_mov_b32 s98, 1.0



; #define PG8_BAR __builtin_amdgcn_s_barrier()
; template <class Epi, class Sched, bool ALIGN_EPI = false, bool SP2 = false>
; __device__ __forceinline__ void gemm_phase(PG8_LAS unsigned char* lds, const Gemm g, const Sched& S, const Epi& E) {
;     ...
;         if constexpr (ALIGN_EPI) { if (wr == 0) PG8_BAR; }
.LBB0_119:
	s_bitcmp1_b32 s68, 0
	s_cbranch_scc0 .Lal_p1
	s_barrier

; #define PG8_STAGE(bufoff, gbase, voff) do { _Pragma("unroll") for (int _i = 0; _i < 2; ++_i) \
;         __builtin_amdgcn_global_load_lds((const unsigned*)((const char*)(gbase) + (voff)[_i]), (PG8_LAS unsigned*)(lds + (bufoff) + ldsw + _i * 8192), 16, 0, 0); } while (0)
; #define PG8_LDA(dst, b, h) do { _Pragma("unroll") for (int m = 0; m < 4; ++m) _Pragma("unroll") for (int k = 0; k < 2; ++k) dst[m][k] = *(const PG8_LAS bf16x8*)(lds + PG8_SA(b, h) + aoff + m * 2048 + k * 1024); } while (0)
; #define PG8_MMA(ai, bj, At, Bt) do { __builtin_amdgcn_s_setprio(1); _Pragma("unroll") for (int m = 0; m < 4; ++m) _Pragma("unroll") for (int n = 0; n < 2; ++n) _Pragma("unroll") for (int k = 0; k < 2; ++k) \
;         acc[ai][bj][m][n] = __builtin_amdgcn_mfma_f32_16x16x32_bf16(Bt[n][k], At[m][k], acc[ai][bj][m][n], 0, 0, 0); __builtin_amdgcn_s_setprio(0); } while (0)
; #define PG8_WAIT_V(n) asm volatile("s_waitcnt vmcnt(" #n ")" ::: "memory")
; #define PG8_WAIT_L(n) asm volatile("s_waitcnt lgkmcnt(" #n ")" ::: "memory")
; #define PG8_BAR __builtin_amdgcn_s_barrier()
; #define PG8_SCHED __builtin_amdgcn_sched_barrier(0)
; template <class Epi, class Sched, bool ALIGN_EPI = false, bool SP2 = false>
; __device__ __forceinline__ void gemm_phase(PG8_LAS unsigned char* lds, const Gemm g, const Sched& S, const Epi& E) {
;     ...
;             PG8_LDA(At, 1, 1); PG8_STAGE(PG8_SB(1, 0), b3, voffB); PG8_STAGE(PG8_SB(1, 1), b3 + hstep, voffB); PG8_STAGE(PG8_SA(1, 0), a3, voffA);
;             PG8_WAIT_V(8); PG8_WAIT_L(0); PG8_BAR; PG8_MMA(1, 0, At, B0); PG8_MMA(1, 1, At, B1); PG8_BAR; PG8_SCHED;
;     ...
;         if constexpr (ALIGN_EPI) { if (wr == 0) PG8_BAR; }
.Lnl_646_7:
	s_barrier
	s_waitcnt lgkmcnt(0)
	v_mfma_f32_16x16x32_bf16 v[62:65], v[148:151], v[184:187], v[62:65]
	v_mfma_f32_16x16x32_bf16 v[58:61], v[160:163], v[184:187], v[58:61]
	v_mfma_f32_16x16x32_bf16 v[46:49], v[148:151], v[192:195], v[46:49]
	v_mfma_f32_16x16x32_bf16 v[42:45], v[160:163], v[192:195], v[42:45]
	v_mfma_f32_16x16x32_bf16 v[30:33], v[148:151], v[200:203], v[30:33]
	v_mfma_f32_16x16x32_bf16 v[26:29], v[160:163], v[200:203], v[26:29]
	v_mfma_f32_16x16x32_bf16 v[14:17], v[148:151], v[212:215], v[14:17]
	v_mfma_f32_16x16x32_bf16 v[10:13], v[160:163], v[212:215], v[10:13]
	v_mfma_f32_16x16x32_bf16 v[62:65], v[156:159], v[188:191], v[62:65]
	v_mfma_f32_16x16x32_bf16 v[58:61], v[164:167], v[188:191], v[58:61]
	v_mfma_f32_16x16x32_bf16 v[46:49], v[156:159], v[196:199], v[46:49]
	v_mfma_f32_16x16x32_bf16 v[42:45], v[164:167], v[196:199], v[42:45]
	v_mfma_f32_16x16x32_bf16 v[30:33], v[156:159], v[208:211], v[30:33]
	v_mfma_f32_16x16x32_bf16 v[26:29], v[164:167], v[208:211], v[26:29]
	v_mfma_f32_16x16x32_bf16 v[14:17], v[156:159], v[216:219], v[14:17]
	v_mfma_f32_16x16x32_bf16 v[10:13], v[164:167], v[216:219], v[10:13]
	v_mfma_f32_16x16x32_bf16 v[54:57], v[168:171], v[184:187], v[54:57]
	v_mfma_f32_16x16x32_bf16 v[50:53], v[176:179], v[184:187], v[50:53]
	v_mfma_f32_16x16x32_bf16 v[38:41], v[168:171], v[192:195], v[38:41]
	v_mfma_f32_16x16x32_bf16 v[34:37], v[176:179], v[192:195], v[34:37]
	v_mfma_f32_16x16x32_bf16 v[22:25], v[168:171], v[200:203], v[22:25]
	v_mfma_f32_16x16x32_bf16 v[18:21], v[176:179], v[200:203], v[18:21]
	v_mfma_f32_16x16x32_bf16 v[6:9], v[168:171], v[212:215], v[6:9]
	v_mfma_f32_16x16x32_bf16 v[2:5], v[176:179], v[212:215], v[2:5]
	v_mfma_f32_16x16x32_bf16 v[54:57], v[172:175], v[188:191], v[54:57]
	v_mfma_f32_16x16x32_bf16 v[50:53], v[180:183], v[188:191], v[50:53]
	v_mfma_f32_16x16x32_bf16 v[38:41], v[172:175], v[196:199], v[38:41]
	v_mfma_f32_16x16x32_bf16 v[34:37], v[180:183], v[196:199], v[34:37]
	v_mfma_f32_16x16x32_bf16 v[22:25], v[172:175], v[208:211], v[22:25]
	v_mfma_f32_16x16x32_bf16 v[18:21], v[180:183], v[208:211], v[18:21]
	v_mfma_f32_16x16x32_bf16 v[6:9], v[172:175], v[216:219], v[6:9]
	v_mfma_f32_16x16x32_bf16 v[2:5], v[180:183], v[216:219], v[2:5]
	s_add_i32 s73, s73, 2
	s_add_u32 s44, s44, 0x100
	s_addc_u32 s45, s45, 0
	s_add_u32 s71, s71, 0x100
	s_addc_u32 s72, s72, 0
	s_cmp_gt_u32 s73, 13
	s_barrier
	s_cbranch_scc0 .LBB0_646


; __device__ __forceinline__ unsigned cvt_pk_bf16(float lo, float hi) { f32x2 v = {lo, hi}; return __builtin_bit_cast(unsigned, __builtin_convertvector(v, nbf16x2e)); }
; #define PG8_BAR __builtin_amdgcn_s_barrier()
; template <class Epi, class Sched, bool ALIGN_EPI = false, bool SP2 = false>
; __device__ __forceinline__ void gemm_phase(PG8_LAS unsigned char* lds, const Gemm g, const Sched& S, const Epi& E) {
;     ...
;         if constexpr (ALIGN_EPI) { if (wr == 0) PG8_BAR; }
;     __device__ __forceinline__ void operator()(const f32x4 (&acc)[2][2][4][2], const Unit& u, int wr, int wc, int fr, int fq) const {
;         const int row0 = u.pm * BM + wr * 64 + fr;
; #pragma unroll
;         for (int ai = 0; ai < 2; ++ai)
; #pragma unroll
;             for (int m = 0; m < 4; ++m) {
;                 const int row = row0 + ai * HALF + m * 16; float ss = 0.f;
; #pragma unroll
;                 for (int bj = 0; bj < 2; ++bj) {
;                     const size_t off = (size_t)row * 1024 + u.pn * BM + bj * HALF + wc * 32 + 8 * fq;
;                     const u32x4 xw = *(const u32x4*)(x + off);
;                     f32x4 x0, x1;
;                     x0[0] = __builtin_bit_cast(float, xw.x << 16); x0[1] = __builtin_bit_cast(float, xw.x & 0xffff0000u); x0[2] = __builtin_bit_cast(float, xw.y << 16); x0[3] = __builtin_bit_cast(float, xw.y & 0xffff0000u);
;                     x1[0] = __builtin_bit_cast(float, xw.z << 16); x1[1] = __builtin_bit_cast(float, xw.z & 0xffff0000u); x1[2] = __builtin_bit_cast(float, xw.w << 16); x1[3] = __builtin_bit_cast(float, xw.w & 0xffff0000u);
;                     const f32x4 h0 = x0 + acc[ai][bj][m][0], h1 = x1 + acc[ai][bj][m][1];
;                     u32x4 w; w.x = cvt_pk_bf16(h0[0], h0[1]); w.y = cvt_pk_bf16(h0[2], h0[3]); w.z = cvt_pk_bf16(h1[0], h1[1]); w.w = cvt_pk_bf16(h1[2], h1[3]);
;                     *(u32x4*)(hb + off) = w;
;                     ss += ((h0[0] * h0[0] + h0[1] * h0[1]) + (h0[2] * h0[2] + h0[3] * h0[3])) + ((h1[0] * h1[0] + h1[1] * h1[1]) + (h1[2] * h1[2] + h1[3] * h1[3]));
;                 }
;                 ss += __shfl_xor(ss, 16); ss += __shfl_xor(ss, 32);
;                 if (fq == 0) part[(size_t)row * 16 + u.pn * 4 + wc] = ss;
;             }
.LBB0_649:
	v_lshl_add_u32 v150, s26, 8, v1
	s_lshl_b32 s19, s10, 8
	s_ashr_i32 s21, s19, 31
	v_ashrrev_i32_e32 v151, 31, v150
	v_mov_b32_e32 v149, s21
	v_or_b32_e32 v148, s19, v138
	v_lshlrev_b64 v[156:157], 10, v[150:151]
	v_lshl_add_u64 v[156:157], v[156:157], 0, v[148:149]
	v_lshlrev_b64 v[166:167], 1, v[156:157]
	v_lshl_add_u64 v[156:157], s[40:41], 0, v[166:167]
	v_lshl_add_u64 v[168:169], s[42:43], 0, v[166:167]
	v_or_b32_e32 v166, 0x100, v166
	global_load_dwordx4 v[158:161], v[156:157], off
	v_lshl_add_u64 v[156:157], s[40:41], 0, v[166:167]
	global_load_dwordx4 v[162:165], v[156:157], off
	v_and_b32_e32 v157, 64, v155
	v_xor_b32_e32 v156, 16, v155
	v_add_u32_e32 v157, 64, v157
	v_xor_b32_e32 v170, 32, v155
	v_cmp_lt_i32_e32 vcc, v156, v157
	s_lshl_b32 s26, s10, 2
	s_ashr_i32 s27, s26, 31
	v_cndmask_b32_e32 v156, v155, v156, vcc
	v_cmp_lt_i32_e32 vcc, v170, v157
	v_lshlrev_b32_e32 v157, 2, v156
	s_bitcmp1_b32 s16, 0
	s_cbranch_scc0 .Lal_p4
	s_barrier
.Lal_p4:
	s_waitcnt vmcnt(0)
	v_and_b32_e32 v171, 0xffff0000, v158
	v_cndmask_b32_e32 v170, v155, v170, vcc
	v_lshlrev_b32_e32 v156, 2, v170
	v_lshlrev_b32_e32 v170, 16, v158
	v_lshlrev_b32_e32 v158, 16, v159
	v_and_b32_e32 v159, 0xffff0000, v159
	v_lshlrev_b32_e32 v172, 16, v160
	v_and_b32_e32 v173, 0xffff0000, v160
	v_lshlrev_b32_e32 v160, 16, v161
	v_and_b32_e32 v161, 0xffff0000, v161
	v_pk_add_f32 v[128:129], v[128:129], v[158:159]
	v_pk_add_f32 v[126:127], v[126:127], v[170:171]
	v_pk_add_f32 v[158:159], v[124:125], v[160:161]
	v_pk_add_f32 v[160:161], v[122:123], v[172:173]
	v_lshlrev_b32_e32 v170, 16, v162
	v_and_b32_e32 v171, 0xffff0000, v162
	v_lshlrev_b32_e32 v162, 16, v163
	v_and_b32_e32 v163, 0xffff0000, v163
	v_lshlrev_b32_e32 v172, 16, v164
	v_and_b32_e32 v173, 0xffff0000, v164
	v_lshlrev_b32_e32 v164, 16, v165
	v_and_b32_e32 v165, 0xffff0000, v165
	v_pk_add_f32 v[120:121], v[120:121], v[162:163]
	v_pk_add_f32 v[118:119], v[118:119], v[170:171]
	v_pk_add_f32 v[162:163], v[116:117], v[164:165]
	v_pk_add_f32 v[164:165], v[114:115], v[172:173]
	v_cvt_pk_bf16_f32 v122, v126, v127
	v_cvt_pk_bf16_f32 v123, v128, v129
	v_cvt_pk_bf16_f32 v124, v160, v161
	v_mul_f32_e32 v125, v127, v127
	v_mul_f32_e32 v127, v129, v129
	v_mul_f32_e32 v129, v161, v161
	v_mul_f32_e32 v161, v159, v159
	v_mul_f32_e32 v114, v119, v119
	v_mul_f32_e32 v115, v121, v121
	v_mul_f32_e32 v116, v165, v165
	v_mul_f32_e32 v117, v163, v163
	v_fmac_f32_e32 v125, v126, v126
	v_fmac_f32_e32 v127, v128, v128
	v_fmac_f32_e32 v129, v160, v160
	v_fmac_f32_e32 v161, v158, v158
	v_fmac_f32_e32 v114, v118, v118
	v_fmac_f32_e32 v115, v120, v120
	v_fmac_f32_e32 v116, v164, v164
	v_fmac_f32_e32 v117, v162, v162
	v_add_f32_e32 v125, v125, v127
	v_add_f32_e32 v126, v129, v161
	v_add_f32_e32 v114, v114, v115
	v_add_f32_e32 v115, v116, v117
	v_add_f32_e32 v125, v125, v126
	v_add_f32_e32 v114, v114, v115
	v_add_f32_e32 v114, v125, v114
	ds_bpermute_b32 v115, v157, v114
	v_cvt_pk_bf16_f32 v125, v158, v159
	v_cvt_pk_bf16_f32 v116, v118, v119
	v_cvt_pk_bf16_f32 v117, v120, v121
	v_cvt_pk_bf16_f32 v118, v164, v165
	s_waitcnt lgkmcnt(0)
	v_add_f32_e32 v114, v114, v115
	ds_bpermute_b32 v115, v156, v114
	v_cvt_pk_bf16_f32 v119, v162, v163
	v_lshl_add_u64 v[120:121], s[42:43], 0, v[166:167]
	global_store_dwordx4 v[168:169], v[122:125], off
	global_store_dwordx4 v[120:121], v[116:119], off
	s_and_saveexec_b64 s[44:45], s[4:5]
	s_cbranch_execz .LBB0_651
	v_lshlrev_b64 v[116:117], 6, v[150:151]
	v_lshl_add_u64 v[116:117], s[8:9], 0, v[116:117]
	v_lshl_add_u64 v[116:117], s[26:27], 2, v[116:117]
	s_lshl_b32 s10, s61, 2
	v_lshl_add_u64 v[116:117], v[116:117], 0, s[10:11]
	s_waitcnt lgkmcnt(0)
	v_add_f32_e32 v114, v114, v115
	global_store_dword v[116:117], v114, off

; #define PG8_STAGE(bufoff, gbase, voff) do { _Pragma("unroll") for (int _i = 0; _i < 2; ++_i) \
;         __builtin_amdgcn_global_load_lds((const unsigned*)((const char*)(gbase) + (voff)[_i]), (PG8_LAS unsigned*)(lds + (bufoff) + ldsw + _i * 8192), 16, 0, 0); } while (0)
; #define PG8_LDA(dst, b, h) do { _Pragma("unroll") for (int m = 0; m < 4; ++m) _Pragma("unroll") for (int k = 0; k < 2; ++k) dst[m][k] = *(const PG8_LAS bf16x8*)(lds + PG8_SA(b, h) + aoff + m * 2048 + k * 1024); } while (0)
; #define PG8_MMA(ai, bj, At, Bt) do { __builtin_amdgcn_s_setprio(1); _Pragma("unroll") for (int m = 0; m < 4; ++m) _Pragma("unroll") for (int n = 0; n < 2; ++n) _Pragma("unroll") for (int k = 0; k < 2; ++k) \
;         acc[ai][bj][m][n] = __builtin_amdgcn_mfma_f32_16x16x32_bf16(Bt[n][k], At[m][k], acc[ai][bj][m][n], 0, 0, 0); __builtin_amdgcn_s_setprio(0); } while (0)
; #define PG8_WAIT_V(n) asm volatile("s_waitcnt vmcnt(" #n ")" ::: "memory")
; #define PG8_WAIT_L(n) asm volatile("s_waitcnt lgkmcnt(" #n ")" ::: "memory")
; #define PG8_BAR __builtin_amdgcn_s_barrier()
; #define PG8_SCHED __builtin_amdgcn_sched_barrier(0)
; template <class Epi, class Sched, bool ALIGN_EPI = false, bool SP2 = false>
; __device__ __forceinline__ void gemm_phase(PG8_LAS unsigned char* lds, const Gemm g, const Sched& S, const Epi& E) {
;     ...
;             PG8_LDA(At, 1, 1); PG8_STAGE(PG8_SB(1, 0), b3, voffB); PG8_STAGE(PG8_SB(1, 1), b3 + hstep, voffB); PG8_STAGE(PG8_SA(1, 0), a3, voffA);
;             PG8_WAIT_V(8); PG8_WAIT_L(0); PG8_BAR; PG8_MMA(1, 0, At, B0); PG8_MMA(1, 1, At, B1); PG8_BAR; PG8_SCHED;
;     ...
;         if constexpr (ALIGN_EPI) { if (wr == 0) PG8_BAR; }
.Lnl_861_7:
	s_barrier
	s_waitcnt lgkmcnt(0)
	v_mfma_f32_16x16x32_bf16 v[60:63], v[146:149], v[184:187], v[60:63]
	v_mfma_f32_16x16x32_bf16 v[56:59], v[160:163], v[184:187], v[56:59]
	v_mfma_f32_16x16x32_bf16 v[44:47], v[146:149], v[192:195], v[44:47]
	v_mfma_f32_16x16x32_bf16 v[40:43], v[160:163], v[192:195], v[40:43]
	v_mfma_f32_16x16x32_bf16 v[28:31], v[146:149], v[200:203], v[28:31]
	v_mfma_f32_16x16x32_bf16 v[24:27], v[160:163], v[200:203], v[24:27]
	v_mfma_f32_16x16x32_bf16 v[12:15], v[146:149], v[208:211], v[12:15]
	v_mfma_f32_16x16x32_bf16 v[8:11], v[160:163], v[208:211], v[8:11]
	v_mfma_f32_16x16x32_bf16 v[60:63], v[156:159], v[188:191], v[60:63]
	v_mfma_f32_16x16x32_bf16 v[56:59], v[164:167], v[188:191], v[56:59]
	v_mfma_f32_16x16x32_bf16 v[44:47], v[156:159], v[196:199], v[44:47]
	v_mfma_f32_16x16x32_bf16 v[40:43], v[164:167], v[196:199], v[40:43]
	v_mfma_f32_16x16x32_bf16 v[28:31], v[156:159], v[204:207], v[28:31]
	v_mfma_f32_16x16x32_bf16 v[24:27], v[164:167], v[204:207], v[24:27]
	v_mfma_f32_16x16x32_bf16 v[12:15], v[156:159], v[212:215], v[12:15]
	v_mfma_f32_16x16x32_bf16 v[8:11], v[164:167], v[212:215], v[8:11]
	v_mfma_f32_16x16x32_bf16 v[52:55], v[168:171], v[184:187], v[52:55]
	v_mfma_f32_16x16x32_bf16 v[48:51], v[176:179], v[184:187], v[48:51]
	v_mfma_f32_16x16x32_bf16 v[36:39], v[168:171], v[192:195], v[36:39]
	v_mfma_f32_16x16x32_bf16 v[32:35], v[176:179], v[192:195], v[32:35]
	v_mfma_f32_16x16x32_bf16 v[20:23], v[168:171], v[200:203], v[20:23]
	v_mfma_f32_16x16x32_bf16 v[16:19], v[176:179], v[200:203], v[16:19]
	v_mfma_f32_16x16x32_bf16 v[4:7], v[168:171], v[208:211], v[4:7]
	v_mfma_f32_16x16x32_bf16 v[0:3], v[176:179], v[208:211], v[0:3]
	v_mfma_f32_16x16x32_bf16 v[52:55], v[172:175], v[188:191], v[52:55]
	v_mfma_f32_16x16x32_bf16 v[48:51], v[180:183], v[188:191], v[48:51]
	v_mfma_f32_16x16x32_bf16 v[36:39], v[172:175], v[196:199], v[36:39]
	v_mfma_f32_16x16x32_bf16 v[32:35], v[180:183], v[196:199], v[32:35]
	v_mfma_f32_16x16x32_bf16 v[20:23], v[172:175], v[204:207], v[20:23]
	v_mfma_f32_16x16x32_bf16 v[16:19], v[180:183], v[204:207], v[16:19]
	v_mfma_f32_16x16x32_bf16 v[4:7], v[172:175], v[212:215], v[4:7]
	v_mfma_f32_16x16x32_bf16 v[0:3], v[180:183], v[212:215], v[0:3]
	s_add_i32 s53, s53, 2
	s_add_u32 s24, s24, 0x100
	s_addc_u32 s25, s25, 0
	s_add_u32 s51, s51, 0x100
	s_addc_u32 s52, s52, 0
	s_cmp_gt_u32 s53, 41
	s_barrier
	s_cbranch_scc0 .LBB0_861


; #define PG8_BAR __builtin_amdgcn_s_barrier()
; template <class Epi, class Sched, bool ALIGN_EPI = false, bool SP2 = false>
; __device__ __forceinline__ void gemm_phase(PG8_LAS unsigned char* lds, const Gemm g, const Sched& S, const Epi& E) {
;     ...
;         if constexpr (ALIGN_EPI) { if (wr == 0) PG8_BAR; }
;     __device__ __forceinline__ void operator()(const f32x4 (&acc)[2][2][4][2], const Unit& u, int wr, int wc, int fr, int fq) const {
;         const int row0 = u.pm * BM + wr * 64 + fr;
; #pragma unroll
;         for (int ai = 0; ai < 2; ++ai)
; #pragma unroll
;             for (int m = 0; m < 4; ++m) {
;                 const int row = row0 + ai * HALF + m * 16;
; #pragma unroll
;                 for (int bj = 0; bj < 2; ++bj) {
;                     const size_t off = (size_t)row * 1024 + u.pn * BM + bj * HALF + wc * 32 + 8 * fq;
;                     const u32x4 hw = *(const u32x4*)(hb + off);
;                     f32x4 h0, h1;
;                     h0[0] = __builtin_bit_cast(float, hw.x << 16); h0[1] = __builtin_bit_cast(float, hw.x & 0xffff0000u); h0[2] = __builtin_bit_cast(float, hw.y << 16); h0[3] = __builtin_bit_cast(float, hw.y & 0xffff0000u);
;                     h1[0] = __builtin_bit_cast(float, hw.z << 16); h1[1] = __builtin_bit_cast(float, hw.z & 0xffff0000u); h1[2] = __builtin_bit_cast(float, hw.w << 16); h1[3] = __builtin_bit_cast(float, hw.w & 0xffff0000u);
;                     __builtin_nontemporal_store(h0 + acc[ai][bj][m][0], (f32x4*)(out + off));
;                     __builtin_nontemporal_store(h1 + acc[ai][bj][m][1], (f32x4*)(out + off + 4));
;                 }
.LBB0_864:
	v_lshl_add_u32 v150, s49, 8, v137
	s_lshl_b32 s24, s50, 8
	s_ashr_i32 s25, s24, 31
	v_ashrrev_i32_e32 v151, 31, v150
	v_mov_b32_e32 v149, s25
	v_or_b32_e32 v148, s24, v136
	v_lshlrev_b64 v[146:147], 10, v[150:151]
	v_lshl_add_u64 v[146:147], v[146:147], 0, v[148:149]
	v_lshlrev_b64 v[160:161], 1, v[146:147]
	v_lshl_add_u64 v[156:157], s[42:43], 0, v[160:161]
	global_load_dwordx4 v[156:159], v[156:157], off
	v_lshl_add_u64 v[162:163], v[146:147], 2, s[54:55]
	v_or_b32_e32 v160, 0x100, v160
	v_lshl_add_u64 v[160:161], s[42:43], 0, v[160:161]
	s_and_b64 vcc, exec, s[0:1]
	s_mov_b64 s[0:1], -1
	s_bitcmp1_b32 s12, 0
	s_cbranch_scc0 .Lal_p6
	s_barrier
.Lal_p6:
	s_waitcnt vmcnt(0)
	v_lshlrev_b32_e32 v164, 16, v156
	v_and_b32_e32 v165, 0xffff0000, v156
	v_lshlrev_b32_e32 v156, 16, v157
	v_and_b32_e32 v157, 0xffff0000, v157
	v_lshlrev_b32_e32 v166, 16, v158
	v_and_b32_e32 v167, 0xffff0000, v158
	v_lshlrev_b32_e32 v158, 16, v159
	v_and_b32_e32 v159, 0xffff0000, v159
	v_pk_add_f32 v[126:127], v[126:127], v[156:157]
	v_pk_add_f32 v[124:125], v[124:125], v[164:165]
	v_pk_add_f32 v[122:123], v[122:123], v[158:159]
	v_pk_add_f32 v[120:121], v[120:121], v[166:167]
	global_store_dwordx4 v[162:163], v[124:127], off nt
	global_store_dwordx4 v[162:163], v[120:123], off offset:16 nt
	global_load_dwordx4 v[120:123], v[160:161], off
	v_or_b32_e32 v124, 16, v150
	v_ashrrev_i32_e32 v125, 31, v124
	v_lshlrev_b64 v[124:125], 10, v[124:125]
	v_lshl_add_u64 v[124:125], v[124:125], 0, v[148:149]
	v_lshlrev_b64 v[126:127], 1, v[124:125]
	v_lshl_add_u64 v[156:157], s[42:43], 0, v[126:127]
	v_or_b32_e32 v126, 0x100, v126
	s_waitcnt vmcnt(0)
	v_lshlrev_b32_e32 v158, 16, v120
	v_and_b32_e32 v159, 0xffff0000, v120
	v_lshlrev_b32_e32 v120, 16, v121
	v_and_b32_e32 v121, 0xffff0000, v121
	v_lshlrev_b32_e32 v160, 16, v122
	v_and_b32_e32 v161, 0xffff0000, v122
	v_lshlrev_b32_e32 v122, 16, v123
	v_and_b32_e32 v123, 0xffff0000, v123
	v_pk_add_f32 v[118:119], v[118:119], v[120:121]
	v_pk_add_f32 v[116:117], v[116:117], v[158:159]
	v_pk_add_f32 v[114:115], v[114:115], v[122:123]
	v_pk_add_f32 v[112:113], v[112:113], v[160:161]
	global_store_dwordx4 v[162:163], v[116:119], off offset:512 nt
	global_store_dwordx4 v[162:163], v[112:115], off offset:528 nt
	global_load_dwordx4 v[112:115], v[156:157], off
	v_lshl_add_u64 v[116:117], v[124:125], 2, s[54:55]
	v_lshl_add_u64 v[118:119], s[42:43], 0, v[126:127]
	s_waitcnt vmcnt(0)
	v_lshlrev_b32_e32 v120, 16, v112
	v_and_b32_e32 v121, 0xffff0000, v112
	v_lshlrev_b32_e32 v112, 16, v113
	v_and_b32_e32 v113, 0xffff0000, v113
	v_lshlrev_b32_e32 v122, 16, v114
	v_and_b32_e32 v123, 0xffff0000, v114
	v_lshlrev_b32_e32 v114, 16, v115
	v_and_b32_e32 v115, 0xffff0000, v115
	v_pk_add_f32 v[110:111], v[110:111], v[112:113]
	v_pk_add_f32 v[108:109], v[108:109], v[120:121]
	v_pk_add_f32 v[106:107], v[106:107], v[114:115]
	v_pk_add_f32 v[104:105], v[104:105], v[122:123]
	global_store_dwordx4 v[116:117], v[108:111], off nt
	global_store_dwordx4 v[116:117], v[104:107], off offset:16 nt
	global_load_dwordx4 v[104:107], v[118:119], off
	v_or_b32_e32 v108, 32, v150
	v_ashrrev_i32_e32 v109, 31, v108
	v_lshlrev_b64 v[108:109], 10, v[108:109]
	v_lshl_add_u64 v[108:109], v[108:109], 0, v[148:149]
	v_lshlrev_b64 v[110:111], 1, v[108:109]
	v_lshl_add_u64 v[112:113], s[42:43], 0, v[110:111]
	v_or_b32_e32 v110, 0x100, v110
	s_waitcnt vmcnt(0)
	v_lshlrev_b32_e32 v114, 16, v104
	v_and_b32_e32 v115, 0xffff0000, v104
	v_lshlrev_b32_e32 v104, 16, v105
	v_and_b32_e32 v105, 0xffff0000, v105
	v_lshlrev_b32_e32 v118, 16, v106
	v_and_b32_e32 v119, 0xffff0000, v106
	v_lshlrev_b32_e32 v106, 16, v107
	v_and_b32_e32 v107, 0xffff0000, v107
	v_pk_add_f32 v[102:103], v[102:103], v[104:105]
	v_pk_add_f32 v[100:101], v[100:101], v[114:115]
	v_pk_add_f32 v[98:99], v[98:99], v[106:107]
	v_pk_add_f32 v[96:97], v[96:97], v[118:119]
	global_store_dwordx4 v[116:117], v[100:103], off offset:512 nt
	global_store_dwordx4 v[116:117], v[96:99], off offset:528 nt
	global_load_dwordx4 v[96:99], v[112:113], off
	v_lshl_add_u64 v[100:101], v[108:109], 2, s[54:55]
	v_lshl_add_u64 v[102:103], s[42:43], 0, v[110:111]
	s_waitcnt vmcnt(0)
	v_lshlrev_b32_e32 v104, 16, v96
	v_and_b32_e32 v105, 0xffff0000, v96
	v_lshlrev_b32_e32 v96, 16, v97
	v_and_b32_e32 v97, 0xffff0000, v97
	v_lshlrev_b32_e32 v106, 16, v98
	v_and_b32_e32 v107, 0xffff0000, v98
	v_lshlrev_b32_e32 v98, 16, v99
	v_and_b32_e32 v99, 0xffff0000, v99
	v_pk_add_f32 v[94:95], v[94:95], v[96:97]
	v_pk_add_f32 v[92:93], v[92:93], v[104:105]
	v_pk_add_f32 v[90:91], v[90:91], v[98:99]
	v_pk_add_f32 v[88:89], v[88:89], v[106:107]
	global_store_dwordx4 v[100:101], v[92:95], off nt
	global_store_dwordx4 v[100:101], v[88:91], off offset:16 nt
	global_load_dwordx4 v[88:91], v[102:103], off
	v_or_b32_e32 v92, 48, v150
	v_ashrrev_i32_e32 v93, 31, v92
	v_lshlrev_b64 v[92:93], 10, v[92:93]
	v_lshl_add_u64 v[92:93], v[92:93], 0, v[148:149]
	v_lshlrev_b64 v[94:95], 1, v[92:93]
	v_lshl_add_u64 v[96:97], s[42:43], 0, v[94:95]
	v_or_b32_e32 v94, 0x100, v94
	s_waitcnt vmcnt(0)
	v_lshlrev_b32_e32 v98, 16, v88
	v_and_b32_e32 v99, 0xffff0000, v88
	v_lshlrev_b32_e32 v88, 16, v89
	v_and_b32_e32 v89, 0xffff0000, v89
	v_lshlrev_b32_e32 v102, 16, v90
	v_and_b32_e32 v103, 0xffff0000, v90
	v_lshlrev_b32_e32 v90, 16, v91
	v_and_b32_e32 v91, 0xffff0000, v91
	v_pk_add_f32 v[86:87], v[86:87], v[88:89]
	v_pk_add_f32 v[84:85], v[84:85], v[98:99]
	v_pk_add_f32 v[82:83], v[82:83], v[90:91]
	v_pk_add_f32 v[80:81], v[80:81], v[102:103]
	global_store_dwordx4 v[100:101], v[84:87], off offset:512 nt
	global_store_dwordx4 v[100:101], v[80:83], off offset:528 nt
	global_load_dwordx4 v[80:83], v[96:97], off
	v_lshl_add_u64 v[84:85], v[92:93], 2, s[54:55]
	v_lshl_add_u64 v[86:87], s[42:43], 0, v[94:95]
	s_waitcnt vmcnt(0)
;     __device__ __forceinline__ void operator()(const f32x4 (&acc)[2][2][4][2], const Unit& u, int wr, int wc, int fr, int fq) const {
;     ...
;                 const int row = row0 + ai * HALF + m * 16;
; #pragma unroll
;                 for (int bj = 0; bj < 2; ++bj) {
;                     const size_t off = (size_t)row * 1024 + u.pn * BM + bj * HALF + wc * 32 + 8 * fq;
;                     const u32x4 hw = *(const u32x4*)(hb + off);
;                     f32x4 h0, h1;
;                     h0[0] = __builtin_bit_cast(float, hw.x << 16); h0[1] = __builtin_bit_cast(float, hw.x & 0xffff0000u); h0[2] = __builtin_bit_cast(float, hw.y << 16); h0[3] = __builtin_bit_cast(float, hw.y & 0xffff0000u);
;                     h1[0] = __builtin_bit_cast(float, hw.z << 16); h1[1] = __builtin_bit_cast(float, hw.z & 0xffff0000u); h1[2] = __builtin_bit_cast(float, hw.w << 16); h1[3] = __builtin_bit_cast(float, hw.w & 0xffff0000u);
;                     __builtin_nontemporal_store(h0 + acc[ai][bj][m][0], (f32x4*)(out + off));
;                     __builtin_nontemporal_store(h1 + acc[ai][bj][m][1], (f32x4*)(out + off + 4));
;                 }
	v_lshlrev_b32_e32 v88, 16, v80
	v_and_b32_e32 v89, 0xffff0000, v80
	v_lshlrev_b32_e32 v80, 16, v81
	v_and_b32_e32 v81, 0xffff0000, v81
	v_lshlrev_b32_e32 v90, 16, v82
	v_and_b32_e32 v91, 0xffff0000, v82
	v_lshlrev_b32_e32 v82, 16, v83
	v_and_b32_e32 v83, 0xffff0000, v83
	v_pk_add_f32 v[78:79], v[78:79], v[80:81]
	v_pk_add_f32 v[76:77], v[76:77], v[88:89]
	v_pk_add_f32 v[74:75], v[74:75], v[82:83]
	v_pk_add_f32 v[72:73], v[72:73], v[90:91]
	global_store_dwordx4 v[84:85], v[76:79], off nt
	global_store_dwordx4 v[84:85], v[72:75], off offset:16 nt
	global_load_dwordx4 v[72:75], v[86:87], off
	v_lshl_add_u64 v[76:77], v[146:147], 0, s[14:15]
	v_lshlrev_b64 v[78:79], 1, v[76:77]
	v_lshl_add_u64 v[80:81], s[42:43], 0, v[78:79]
	v_or_b32_e32 v78, 0x100, v78
	s_waitcnt vmcnt(0)
	v_lshlrev_b32_e32 v82, 16, v72
	v_and_b32_e32 v83, 0xffff0000, v72
	v_lshlrev_b32_e32 v72, 16, v73
	v_and_b32_e32 v73, 0xffff0000, v73
	v_lshlrev_b32_e32 v86, 16, v74
	v_and_b32_e32 v87, 0xffff0000, v74
	v_lshlrev_b32_e32 v74, 16, v75
	v_and_b32_e32 v75, 0xffff0000, v75
	v_pk_add_f32 v[70:71], v[70:71], v[72:73]
	v_pk_add_f32 v[68:69], v[68:69], v[82:83]
	v_pk_add_f32 v[66:67], v[66:67], v[74:75]
	v_pk_add_f32 v[64:65], v[64:65], v[86:87]
	global_store_dwordx4 v[84:85], v[68:71], off offset:512 nt
	global_store_dwordx4 v[84:85], v[64:67], off offset:528 nt
	global_load_dwordx4 v[64:67], v[80:81], off
	v_lshl_add_u64 v[68:69], v[76:77], 2, s[54:55]
	v_lshl_add_u64 v[70:71], s[42:43], 0, v[78:79]
	s_waitcnt vmcnt(0)
	v_lshlrev_b32_e32 v72, 16, v64
	v_and_b32_e32 v73, 0xffff0000, v64
	v_lshlrev_b32_e32 v64, 16, v65
	v_and_b32_e32 v65, 0xffff0000, v65
	v_lshlrev_b32_e32 v74, 16, v66
	v_and_b32_e32 v75, 0xffff0000, v66
	v_lshlrev_b32_e32 v66, 16, v67
	v_and_b32_e32 v67, 0xffff0000, v67
	v_pk_add_f32 v[62:63], v[62:63], v[64:65]
	v_pk_add_f32 v[60:61], v[60:61], v[72:73]
	v_pk_add_f32 v[58:59], v[58:59], v[66:67]
	v_pk_add_f32 v[56:57], v[56:57], v[74:75]
	global_store_dwordx4 v[68:69], v[60:63], off nt
	global_store_dwordx4 v[68:69], v[56:59], off offset:16 nt
	global_load_dwordx4 v[56:59], v[70:71], off
	v_lshl_add_u64 v[60:61], v[146:147], 0, s[16:17]
	v_lshlrev_b64 v[62:63], 1, v[60:61]
	v_lshl_add_u64 v[64:65], s[42:43], 0, v[62:63]
	v_or_b32_e32 v62, 0x100, v62
	s_waitcnt vmcnt(0)
	v_lshlrev_b32_e32 v66, 16, v56
	v_and_b32_e32 v67, 0xffff0000, v56
	v_lshlrev_b32_e32 v56, 16, v57
	v_and_b32_e32 v57, 0xffff0000, v57
	v_lshlrev_b32_e32 v70, 16, v58
	v_and_b32_e32 v71, 0xffff0000, v58
	v_lshlrev_b32_e32 v58, 16, v59
	v_and_b32_e32 v59, 0xffff0000, v59
	v_pk_add_f32 v[54:55], v[54:55], v[56:57]
	v_pk_add_f32 v[52:53], v[52:53], v[66:67]
	v_pk_add_f32 v[50:51], v[50:51], v[58:59]
	v_pk_add_f32 v[48:49], v[48:49], v[70:71]
	global_store_dwordx4 v[68:69], v[52:55], off offset:512 nt
	global_store_dwordx4 v[68:69], v[48:51], off offset:528 nt
	global_load_dwordx4 v[48:51], v[64:65], off
	v_lshl_add_u64 v[52:53], v[60:61], 2, s[54:55]
	v_lshl_add_u64 v[54:55], s[42:43], 0, v[62:63]
	s_waitcnt vmcnt(0)
	v_lshlrev_b32_e32 v56, 16, v48
	v_and_b32_e32 v57, 0xffff0000, v48
	v_lshlrev_b32_e32 v48, 16, v49
	v_and_b32_e32 v49, 0xffff0000, v49
	v_lshlrev_b32_e32 v58, 16, v50
	v_and_b32_e32 v59, 0xffff0000, v50
	v_lshlrev_b32_e32 v50, 16, v51
	v_and_b32_e32 v51, 0xffff0000, v51
	v_pk_add_f32 v[46:47], v[46:47], v[48:49]
	v_pk_add_f32 v[44:45], v[44:45], v[56:57]
	v_pk_add_f32 v[42:43], v[42:43], v[50:51]
	v_pk_add_f32 v[40:41], v[40:41], v[58:59]
	global_store_dwordx4 v[52:53], v[44:47], off nt
	global_store_dwordx4 v[52:53], v[40:43], off offset:16 nt
	global_load_dwordx4 v[40:43], v[54:55], off
	v_lshl_add_u64 v[44:45], v[146:147], 0, s[18:19]
	v_lshlrev_b64 v[46:47], 1, v[44:45]
	v_lshl_add_u64 v[48:49], s[42:43], 0, v[46:47]
	v_or_b32_e32 v46, 0x100, v46
	s_waitcnt vmcnt(0)
; #define PG8_BAR __builtin_amdgcn_s_barrier()
; template <class Epi, class Sched, bool ALIGN_EPI = false, bool SP2 = false>
; __device__ __forceinline__ void gemm_phase(PG8_LAS unsigned char* lds, const Gemm g, const Sched& S, const Epi& E) {
;     ...
;         if constexpr (ALIGN_EPI) { if (wr == 1) PG8_BAR; }
;     __device__ __forceinline__ void operator()(const f32x4 (&acc)[2][2][4][2], const Unit& u, int wr, int wc, int fr, int fq) const {
;     ...
;                 const int row = row0 + ai * HALF + m * 16;
; #pragma unroll
;                 for (int bj = 0; bj < 2; ++bj) {
;                     const size_t off = (size_t)row * 1024 + u.pn * BM + bj * HALF + wc * 32 + 8 * fq;
;                     const u32x4 hw = *(const u32x4*)(hb + off);
;                     f32x4 h0, h1;
;                     h0[0] = __builtin_bit_cast(float, hw.x << 16); h0[1] = __builtin_bit_cast(float, hw.x & 0xffff0000u); h0[2] = __builtin_bit_cast(float, hw.y << 16); h0[3] = __builtin_bit_cast(float, hw.y & 0xffff0000u);
;                     h1[0] = __builtin_bit_cast(float, hw.z << 16); h1[1] = __builtin_bit_cast(float, hw.z & 0xffff0000u); h1[2] = __builtin_bit_cast(float, hw.w << 16); h1[3] = __builtin_bit_cast(float, hw.w & 0xffff0000u);
;                     __builtin_nontemporal_store(h0 + acc[ai][bj][m][0], (f32x4*)(out + off));
;                     __builtin_nontemporal_store(h1 + acc[ai][bj][m][1], (f32x4*)(out + off + 4));
;                 }
	v_lshlrev_b32_e32 v50, 16, v40
	v_and_b32_e32 v51, 0xffff0000, v40
	v_lshlrev_b32_e32 v40, 16, v41
	v_and_b32_e32 v41, 0xffff0000, v41
	v_lshlrev_b32_e32 v54, 16, v42
	v_and_b32_e32 v55, 0xffff0000, v42
	v_lshlrev_b32_e32 v42, 16, v43
	v_and_b32_e32 v43, 0xffff0000, v43
	v_pk_add_f32 v[38:39], v[38:39], v[40:41]
	v_pk_add_f32 v[36:37], v[36:37], v[50:51]
	v_pk_add_f32 v[34:35], v[34:35], v[42:43]
	v_pk_add_f32 v[32:33], v[32:33], v[54:55]
	global_store_dwordx4 v[52:53], v[36:39], off offset:512 nt
	global_store_dwordx4 v[52:53], v[32:35], off offset:528 nt
	global_load_dwordx4 v[32:35], v[48:49], off
	v_lshl_add_u64 v[36:37], v[44:45], 2, s[54:55]
	v_lshl_add_u64 v[38:39], s[42:43], 0, v[46:47]
	s_waitcnt vmcnt(0)
	v_lshlrev_b32_e32 v40, 16, v32
	v_and_b32_e32 v41, 0xffff0000, v32
	v_lshlrev_b32_e32 v32, 16, v33
	v_and_b32_e32 v33, 0xffff0000, v33
	v_lshlrev_b32_e32 v42, 16, v34
	v_and_b32_e32 v43, 0xffff0000, v34
	v_lshlrev_b32_e32 v34, 16, v35
	v_and_b32_e32 v35, 0xffff0000, v35
	v_pk_add_f32 v[30:31], v[30:31], v[32:33]
	v_pk_add_f32 v[28:29], v[28:29], v[40:41]
	v_pk_add_f32 v[26:27], v[26:27], v[34:35]
	v_pk_add_f32 v[24:25], v[24:25], v[42:43]
	global_store_dwordx4 v[36:37], v[28:31], off nt
	global_store_dwordx4 v[36:37], v[24:27], off offset:16 nt
	global_load_dwordx4 v[24:27], v[38:39], off
	v_lshl_add_u64 v[28:29], v[146:147], 0, s[20:21]
	v_lshlrev_b64 v[30:31], 1, v[28:29]
	v_lshl_add_u64 v[32:33], s[42:43], 0, v[30:31]
	v_or_b32_e32 v30, 0x100, v30
	s_waitcnt vmcnt(0)
	v_lshlrev_b32_e32 v34, 16, v24
	v_and_b32_e32 v35, 0xffff0000, v24
	v_lshlrev_b32_e32 v24, 16, v25
	v_and_b32_e32 v25, 0xffff0000, v25
	v_lshlrev_b32_e32 v38, 16, v26
	v_and_b32_e32 v39, 0xffff0000, v26
	v_lshlrev_b32_e32 v26, 16, v27
	v_and_b32_e32 v27, 0xffff0000, v27
	v_pk_add_f32 v[22:23], v[22:23], v[24:25]
	v_pk_add_f32 v[20:21], v[20:21], v[34:35]
	v_pk_add_f32 v[18:19], v[18:19], v[26:27]
	v_pk_add_f32 v[16:17], v[16:17], v[38:39]
	global_store_dwordx4 v[36:37], v[20:23], off offset:512 nt
	global_store_dwordx4 v[36:37], v[16:19], off offset:528 nt
	global_load_dwordx4 v[16:19], v[32:33], off
	v_lshl_add_u64 v[20:21], v[28:29], 2, s[54:55]
	v_lshl_add_u64 v[22:23], s[42:43], 0, v[30:31]
	s_waitcnt vmcnt(0)
	v_lshlrev_b32_e32 v24, 16, v16
	v_and_b32_e32 v25, 0xffff0000, v16
	v_lshlrev_b32_e32 v16, 16, v17
	v_and_b32_e32 v17, 0xffff0000, v17
	v_lshlrev_b32_e32 v26, 16, v18
	v_and_b32_e32 v27, 0xffff0000, v18
	v_lshlrev_b32_e32 v18, 16, v19
	v_and_b32_e32 v19, 0xffff0000, v19
	v_pk_add_f32 v[14:15], v[14:15], v[16:17]
	v_pk_add_f32 v[12:13], v[12:13], v[24:25]
	v_pk_add_f32 v[10:11], v[10:11], v[18:19]
	v_pk_add_f32 v[8:9], v[8:9], v[26:27]
	global_store_dwordx4 v[20:21], v[12:15], off nt
	global_store_dwordx4 v[20:21], v[8:11], off offset:16 nt
	global_load_dwordx4 v[8:11], v[22:23], off
	s_waitcnt vmcnt(0)
	v_lshlrev_b32_e32 v12, 16, v8
	v_and_b32_e32 v13, 0xffff0000, v8
	v_lshlrev_b32_e32 v8, 16, v9
	v_and_b32_e32 v9, 0xffff0000, v9
	v_lshlrev_b32_e32 v14, 16, v10
	v_and_b32_e32 v15, 0xffff0000, v10
	v_lshlrev_b32_e32 v10, 16, v11
	v_and_b32_e32 v11, 0xffff0000, v11
	v_pk_add_f32 v[6:7], v[6:7], v[8:9]
	v_pk_add_f32 v[4:5], v[4:5], v[12:13]
	v_pk_add_f32 v[2:3], v[2:3], v[10:11]
	v_pk_add_f32 v[0:1], v[0:1], v[14:15]
	global_store_dwordx4 v[20:21], v[4:7], off offset:512 nt
	global_store_dwordx4 v[20:21], v[0:3], off offset:528 nt
	s_cbranch_vccnz .LBB0_849
	s_andn2_b64 vcc, exec, s[8:9]
	s_cbranch_vccnz .LBB0_848
	s_barrier
	s_branch .LBB0_848
